# dattn: V loads of each K/V staging round issued right behind the K loads into unused VGPRs instead of after the K LDS writes
# speedup vs baseline: 1.0104x; 1.0014x over previous
.LBB0_1393:
	s_lshr_b32 s0, s5, 5
	s_and_b32 s1, s5, 31
	s_lshr_b32 s97, s1, 4
	s_lshl_b32 s97, s97, 2
	s_and_b32 s2, s0, 3
	s_or_b32 s97, s97, s2
	s_lshr_b32 s0, s0, 2
	s_lshl_b32 s0, s0, 4
	s_and_b32 s1, s1, 15
	s_or_b32 s0, s0, s1
	s_lshl_b32 s88, s0, 8
	s_cmp_lt_i32 s0, 64
	s_movk_i32 s0, 0xe000
	s_cselect_b32 s0, s0, 0x7ffff000
	s_movk_i32 s1, 0x2000
	s_cselect_b32 s2, s1, 0x1000
	s_and_b32 s33, s0, s88
	s_sub_i32 s3, s88, s33
	s_sub_i32 s0, s3, 64
	s_add_i32 s1, s2, -1
	v_add_u32_e32 v0, s0, v91
	v_min_i32_e32 v1, s1, v0
	v_cmp_lt_i32_e32 vcc, -1, v0
	s_lshl_b32 s89, s97, 7
	v_or_b32_e32 v148, s89, v90
	v_cndmask_b32_e32 v0, 0, v1, vcc
	v_add_u32_e32 v0, s33, v0
	v_lshl_add_u32 v24, v0, 10, v148
	v_add_u32_e32 v0, s0, v92
	v_min_i32_e32 v1, s1, v0
	v_cmp_lt_i32_e32 vcc, -1, v0
	v_add_u32_e32 v8, s0, v93
	v_min_i32_e32 v9, s1, v8
	v_cndmask_b32_e32 v0, 0, v1, vcc
	v_cmp_lt_i32_e32 vcc, -1, v8
	v_add_u32_e32 v16, s0, v95
	v_min_i32_e32 v17, s1, v16
	v_cndmask_b32_e32 v8, 0, v9, vcc
	v_add_u32_e32 v8, s33, v8
	v_lshl_add_u32 v26, v8, 10, v148
	v_add_u32_e32 v8, s0, v94
	v_min_i32_e32 v9, s1, v8
	v_cmp_lt_i32_e32 vcc, -1, v8
	v_add_u32_e32 v0, s33, v0
	v_lshl_add_u32 v25, v0, 10, v148
	v_cndmask_b32_e32 v8, 0, v9, vcc
	v_cmp_lt_i32_e32 vcc, -1, v16
	v_add_u32_e32 v8, s33, v8
	global_load_dwordx4 v[0:3], v24, s[92:93]
	global_load_dwordx4 v[4:7], v25, s[92:93]
	v_cndmask_b32_e32 v16, 0, v17, vcc
	v_add_u32_e32 v16, s33, v16
	v_lshl_add_u32 v28, v16, 10, v148
	v_add_u32_e32 v16, s0, v97
	v_min_i32_e32 v17, s1, v16
	v_cmp_lt_i32_e32 vcc, -1, v16
	v_lshl_add_u32 v27, v8, 10, v148
	global_load_dwordx4 v[8:11], v26, s[92:93]
	global_load_dwordx4 v[12:15], v27, s[92:93]
	v_cndmask_b32_e32 v16, 0, v17, vcc
	v_or_b32_e32 v17, s33, v96
	v_add_u32_e32 v16, v17, v16
	v_lshl_add_u32 v29, v16, 10, v148
	global_load_dwordx4 v[16:19], v28, s[92:93]
	global_load_dwordx4 v[20:23], v29, s[92:93]
	global_load_dword v30, v[76:77], off
	global_load_dword v31, v[78:79], off
	global_load_dwordx4 v[210:213], v24, s[94:95]
	global_load_dwordx4 v[214:217], v25, s[94:95]
	global_load_dwordx4 v[218:221], v26, s[94:95]
	global_load_dwordx4 v[222:225], v27, s[94:95]
	global_load_dwordx4 v[226:229], v28, s[94:95]
	global_load_dwordx4 v[230:233], v29, s[94:95]
	v_readlane_b32 s0, v243, 3
	s_add_i32 s0, s3, s0
	v_or_b32_e32 v149, s89, v100
	s_mov_b32 s38, 0
	v_mov_b32_e32 v56, 0
	v_mov_b32_e32 v57, v75
	s_waitcnt vmcnt(6)
	ds_write_b128 v138, v[0:3]
	ds_write_b128 v139, v[4:7]
	ds_write_b128 v138, v[8:11] offset:18432
	ds_write_b128 v140, v[12:15]
	ds_write_b128 v138, v[16:19] offset:36864
	ds_write_b128 v141, v[20:23]
	s_nop 0
	s_nop 0
	s_nop 0
	s_nop 0
	s_nop 0
	s_nop 0
	v_or_b32_e32 v24, s0, v73
	v_or_b32_e32 v25, s0, v72
	v_add_u32_e32 v26, s33, v24
	v_add_u32_e32 v27, s33, v25
	v_lshl_add_u32 v26, v26, 10, v149
	v_lshl_add_u32 v27, v27, 10, v149
	v_or_b32_e32 v36, 64, v26
	v_or_b32_e32 v44, 64, v27
	v_and_b32_e32 v28, 0x7fffffff, v30
	v_and_b32_e32 v29, 0x7fffffff, v31
	ds_bpermute_b32 v28, v81, v28
	ds_bpermute_b32 v29, v81, v29
	v_max_f32_e64 v30, |v30|, |v30|
	v_max_f32_e64 v31, |v31|, |v31|
	s_mul_i32 s0, s97, 0xc000
	s_waitcnt lgkmcnt(1)
	v_max_f32_e32 v28, v28, v28
	s_waitcnt lgkmcnt(0)
	v_max_f32_e32 v29, v29, v29
	v_max_f32_e32 v28, v30, v28
	v_max_f32_e32 v29, v31, v29
	ds_bpermute_b32 v30, v85, v28
	ds_bpermute_b32 v31, v85, v29
	s_waitcnt vmcnt(5)
	ds_write_b128 v138, v[210:213] offset:55296
	s_waitcnt vmcnt(4)
	ds_write_b128 v139, v[214:217] offset:55296
	s_waitcnt vmcnt(3)
	ds_write_b128 v98, v[218:221]
	s_waitcnt vmcnt(2)
	ds_write_b128 v140, v[222:225] offset:55296
	s_waitcnt vmcnt(1)
	ds_write_b128 v99, v[226:229]
	s_waitcnt vmcnt(0)
	ds_write_b128 v141, v[230:233] offset:55296
	s_waitcnt lgkmcnt(0)
	s_barrier
	global_load_dwordx4 v[32:35], v26, s[90:91]
	s_nop 0
	global_load_dwordx4 v[36:39], v36, s[90:91]
	s_nop 0
	global_load_dwordx4 v[40:43], v27, s[90:91]
	s_nop 0
	global_load_dwordx4 v[44:47], v44, s[90:91]
	s_waitcnt lgkmcnt(7)
	v_max_f32_e32 v30, v30, v30
	s_waitcnt lgkmcnt(6)
	v_max_f32_e32 v31, v31, v31
	v_max_f32_e32 v28, v28, v30
	v_max_f32_e32 v29, v29, v31
	ds_bpermute_b32 v30, v86, v28
	ds_bpermute_b32 v31, v86, v29
	v_mov_b32_e32 v4, 0
	v_mov_b32_e32 v5, v75
	v_mov_b32_e32 v6, v75
	s_waitcnt lgkmcnt(1)
	v_max_f32_e32 v0, v30, v30
	v_max_f32_e32 v0, v28, v0
	s_waitcnt lgkmcnt(0)
	v_max_f32_e32 v2, v31, v31
	ds_bpermute_b32 v1, v87, v0
	v_max_f32_e32 v2, v29, v2
	ds_bpermute_b32 v3, v87, v2
	v_mov_b32_e32 v7, v75
	v_mov_b32_e32 v8, 0
	s_waitcnt lgkmcnt(1)
	v_max_f32_e32 v1, v1, v1
	v_max_f32_e32 v0, v0, v1
	s_waitcnt lgkmcnt(0)
	v_max_f32_e32 v3, v3, v3
	ds_bpermute_b32 v1, v88, v0
	v_max_f32_e32 v2, v2, v3
	ds_bpermute_b32 v3, v88, v2
	v_mov_b32_e32 v9, v75
	v_mov_b32_e32 v10, v75
	s_waitcnt lgkmcnt(1)
	v_max_f32_e32 v1, v1, v1
	v_max_f32_e32 v0, v0, v1
	s_waitcnt lgkmcnt(0)
	v_max_f32_e32 v3, v3, v3
	ds_bpermute_b32 v1, v89, v0
	v_max_f32_e32 v2, v2, v3
	ds_bpermute_b32 v3, v89, v2
	v_mov_b32_e32 v11, v75
	v_mov_b32_e32 v12, 0
	s_waitcnt lgkmcnt(1)
	v_max_f32_e32 v1, v1, v1
	v_max_f32_e32 v0, v0, v1
	s_waitcnt lgkmcnt(0)
	v_max_f32_e32 v1, v3, v3
	v_max_f32_e32 v1, v2, v1
	v_mul_f32_e32 v0, 0x41000000, v0
	v_mul_f32_e32 v0, v0, v1
	v_mul_f32_e32 v150, 0x3fb8aa3b, v0
	v_max_i32_e32 v0, 64, v25
	v_max_i32_e32 v1, 64, v24
	v_subrev_u32_e32 v52, 64, v0
	v_add_u32_e32 v0, 64, v24
	v_subrev_u32_e32 v53, 64, v1
	v_min_i32_e32 v0, s1, v0
	v_add_u32_e32 v1, 64, v25
	v_sub_u32_e32 v55, v0, v53
	v_add_u32_e32 v0, s88, v125
	v_min_i32_e32 v1, s1, v1
	v_subrev_u32_e32 v0, s33, v0
	v_sub_u32_e32 v54, v1, v52
	v_mov_b32_e32 v70, v0
	v_mov_b32_e32 v0, 0
	v_mov_b32_e32 v1, v75
	v_mov_b32_e32 v2, v75
	v_mov_b32_e32 v3, v75
	v_mov_b32_e32 v13, v75
	v_mov_b32_e32 v14, v75
	v_mov_b32_e32 v15, v75
	v_mov_b32_e32 v16, 0
	v_mov_b32_e32 v17, v75
	v_mov_b32_e32 v18, v75
	v_mov_b32_e32 v19, v75
	v_mov_b32_e32 v20, 0
	v_mov_b32_e32 v21, v75
	v_mov_b32_e32 v22, v75
	v_mov_b32_e32 v23, v75
	v_mov_b32_e32 v24, 0
	v_mov_b32_e32 v25, v75
	v_mov_b32_e32 v26, v75
	v_mov_b32_e32 v27, v75
	v_mov_b32_e32 v28, 0
	v_mov_b32_e32 v29, v75
	v_mov_b32_e32 v30, v75
	v_mov_b32_e32 v31, v75
.LBB0_1394:
	v_add_u32_e32 v68, s38, v126
	ds_read_b128 v[48:51], v68
	ds_read_b128 v[60:63], v68 offset:2304
	ds_read_b128 v[64:67], v68 offset:64
	ds_read_b128 v[152:155], v68 offset:2368
	v_add_u32_e32 v69, s38, v127
	s_waitcnt vmcnt(3) lgkmcnt(3)
	v_mfma_f32_16x16x32_bf16 v[156:159], v[48:51], v[32:35], 0
	ds_read_b64_tr_b16 v[170:171], v69 offset:57600
	ds_read_b64_tr_b16 v[168:169], v69 offset:55296
	v_sub_u32_e32 v59, v70, v52
	v_sub_u32_e32 v58, v70, v53
	s_waitcnt vmcnt(1)
	v_mfma_f32_16x16x32_bf16 v[164:167], v[48:51], v[40:43], 0
	ds_read_b64_tr_b16 v[172:173], v69 offset:55328
	ds_read_b64_tr_b16 v[176:177], v69 offset:55360
	ds_read_b64_tr_b16 v[48:49], v69 offset:55392
	ds_read_b64_tr_b16 v[174:175], v69 offset:57632
	ds_read_b64_tr_b16 v[178:179], v69 offset:57664
	ds_read_b64_tr_b16 v[50:51], v69 offset:57696
	v_add_u32_e32 v68, 1, v59
	s_waitcnt lgkmcnt(10)
	v_mfma_f32_16x16x32_bf16 v[160:163], v[60:63], v[32:35], 0
	v_add_u32_e32 v71, 1, v58
	v_add_u32_e32 v151, 2, v59
	v_add_u32_e32 v180, 2, v58
	v_mfma_f32_16x16x32_bf16 v[60:63], v[60:63], v[40:43], 0
	v_add_u32_e32 v181, 3, v59
	v_add_u32_e32 v183, 3, v58
	v_add_u32_e32 v184, 16, v59
	s_waitcnt lgkmcnt(9)
	v_mfma_f32_16x16x32_bf16 v[156:159], v[64:67], v[36:39], v[156:159]
	v_add_u32_e32 v185, 16, v58
	v_add_u32_e32 v186, 17, v59
	v_add_u32_e32 v187, 17, v58
	s_waitcnt vmcnt(0)
	v_mfma_f32_16x16x32_bf16 v[64:67], v[64:67], v[44:47], v[164:167]
	v_add_u32_e32 v188, 18, v59
	s_nop 1
	v_fma_f32 v69, v156, s4, -v150
	v_exp_f32_e32 v69, v69
	s_waitcnt lgkmcnt(8)
	v_mfma_f32_16x16x32_bf16 v[160:163], v[152:155], v[36:39], v[160:163]
	v_add_u32_e32 v189, 18, v58
	v_fma_f32 v64, v64, s4, -v150
	v_fma_f32 v65, v65, s4, -v150
	v_mfma_f32_16x16x32_bf16 v[60:63], v[152:155], v[44:47], v[60:63]
	v_fma_f32 v152, v157, s4, -v150
	v_fma_f32 v153, v158, s4, -v150
	v_fma_f32 v154, v159, s4, -v150
	s_nop 0
	v_fma_f32 v155, v160, s4, -v150
	v_fma_f32 v156, v161, s4, -v150
	v_fma_f32 v157, v162, s4, -v150
	v_fma_f32 v158, v163, s4, -v150
	v_fma_f32 v66, v66, s4, -v150
	v_fma_f32 v67, v67, s4, -v150
	v_fma_f32 v60, v60, s4, -v150
	v_fma_f32 v61, v61, s4, -v150
	v_fma_f32 v62, v62, s4, -v150
	v_fma_f32 v63, v63, s4, -v150
	v_exp_f32_e32 v64, v64
	v_exp_f32_e32 v152, v152
	v_exp_f32_e32 v153, v153
	v_exp_f32_e32 v154, v154
	v_exp_f32_e32 v155, v155
	v_exp_f32_e32 v156, v156
	v_exp_f32_e32 v157, v157
	v_exp_f32_e32 v158, v158
	v_exp_f32_e32 v65, v65
	v_exp_f32_e32 v66, v66
	v_exp_f32_e32 v67, v67
	v_exp_f32_e32 v159, v60
	v_exp_f32_e32 v160, v61
	v_exp_f32_e32 v162, v62
	v_exp_f32_e32 v164, v63
	v_add_u32_e32 v190, 19, v59
	v_add_u32_e32 v191, 19, v58
	v_cmp_le_u32_e32 vcc, v59, v54
	v_cmp_le_u32_e64 s[36:37], v58, v55
	v_cmp_le_u32_e64 s[0:1], v71, v55
	v_cmp_le_u32_e64 s[8:9], v68, v54
	v_cmp_le_u32_e64 s[10:11], v180, v55
	v_cmp_le_u32_e64 s[12:13], v151, v54
	v_cmp_le_u32_e64 s[14:15], v183, v55
	v_cmp_le_u32_e64 s[16:17], v181, v54
	v_cmp_le_u32_e64 s[18:19], v185, v55
	v_cmp_le_u32_e64 s[20:21], v184, v54
	v_cmp_le_u32_e64 s[22:23], v187, v55
	v_cmp_le_u32_e64 s[24:25], v186, v54
	v_cmp_le_u32_e64 s[26:27], v189, v55
	v_cmp_le_u32_e64 s[28:29], v188, v54
	v_cmp_le_u32_e64 s[30:31], v191, v55
	v_cmp_le_u32_e64 s[34:35], v190, v54
	v_cndmask_b32_e64 v59, 0, v69, s[36:37]
	v_cndmask_b32_e32 v58, 0, v64, vcc
	v_cndmask_b32_e64 v63, 0, v152, s[0:1]
	v_cndmask_b32_e64 v62, 0, v65, s[8:9]
	v_cndmask_b32_e64 v61, 0, v153, s[10:11]
	v_cndmask_b32_e64 v60, 0, v66, s[12:13]
	v_cndmask_b32_e64 v65, 0, v154, s[14:15]
	v_cndmask_b32_e64 v64, 0, v67, s[16:17]
	v_cndmask_b32_e64 v67, 0, v155, s[18:19]
	v_cndmask_b32_e64 v66, 0, v159, s[20:21]
	v_cndmask_b32_e64 v69, 0, v156, s[22:23]
	v_cndmask_b32_e64 v68, 0, v160, s[24:25]
	v_cndmask_b32_e64 v161, 0, v157, s[26:27]
	v_cndmask_b32_e64 v160, 0, v162, s[28:29]
	v_cndmask_b32_e64 v163, 0, v158, s[30:31]
	v_cndmask_b32_e64 v162, 0, v164, s[34:35]
	v_pk_add_f32 v[56:57], v[56:57], v[58:59]
	v_cvt_pk_bf16_f32 v152, v59, v63
	v_cvt_pk_bf16_f32 v153, v61, v65
	v_cvt_pk_bf16_f32 v154, v67, v69
	v_cvt_pk_bf16_f32 v155, v161, v163
	v_cvt_pk_bf16_f32 v156, v58, v62
	v_cvt_pk_bf16_f32 v157, v60, v64
	v_cvt_pk_bf16_f32 v158, v66, v68
	v_cvt_pk_bf16_f32 v159, v160, v162
	v_pk_add_f32 v[56:57], v[62:63], v[56:57]
	s_waitcnt lgkmcnt(0)
	v_mfma_f32_16x16x32_bf16 v[16:19], v[48:51], v[152:155], v[16:19]
	s_addk_i32 s38, 0x1200
	v_add_u32_e32 v70, 32, v70
	s_cmpk_lg_i32 s38, 0x5a00
	v_mfma_f32_16x16x32_bf16 v[0:3], v[48:51], v[156:159], v[0:3]
	v_add_f32_e64 v48, v60, v56
	v_add_f32_e64 v49, v61, v57
	v_pk_add_f32 v[48:49], v[64:65], v[48:49]
	v_mfma_f32_16x16x32_bf16 v[28:31], v[168:171], v[152:155], v[28:31]
	v_add_f32_e64 v48, v66, v48
	v_add_f32_e64 v49, v67, v49
	v_pk_add_f32 v[48:49], v[68:69], v[48:49]
	v_mfma_f32_16x16x32_bf16 v[12:15], v[168:171], v[156:159], v[12:15]
	v_add_f32_e64 v48, v160, v48
	v_add_f32_e64 v49, v161, v49
	v_pk_add_f32 v[56:57], v[162:163], v[48:49]
	v_mfma_f32_16x16x32_bf16 v[24:27], v[172:175], v[152:155], v[24:27]
	v_mfma_f32_16x16x32_bf16 v[8:11], v[172:175], v[156:159], v[8:11]
	v_mfma_f32_16x16x32_bf16 v[20:23], v[176:179], v[152:155], v[20:23]
	v_mfma_f32_16x16x32_bf16 v[4:7], v[176:179], v[156:159], v[4:7]
	s_cbranch_scc1 .LBB0_1394
	s_ashr_i32 s0, s3, 2
	s_lshr_b32 s1, s2, 2
	s_sub_i32 s8, s0, 64
	s_add_i32 s1, s1, -1
	v_add_u32_e32 v32, s8, v91
	v_min_i32_e32 v33, s1, v32
	v_lshlrev_b32_e32 v33, 2, v33
	v_cmp_lt_i32_e32 vcc, -1, v32
	v_add_u32_e32 v40, s8, v104
	v_min_i32_e32 v41, s1, v40
	v_cndmask_b32_e32 v58, 0, v33, vcc
	v_add_u32_e32 v32, s33, v58
	v_lshl_add_u32 v64, v32, 10, v148
	v_add_u32_e32 v32, s8, v92
	v_min_i32_e32 v33, s1, v32
	v_lshlrev_b32_e32 v33, 2, v33
	v_cmp_lt_i32_e32 vcc, -1, v32
	v_lshlrev_b32_e32 v41, 2, v41
	v_add_u32_e32 v48, s8, v95
	v_cndmask_b32_e32 v59, 0, v33, vcc
	v_cmp_lt_i32_e32 vcc, -1, v40
	v_or_b32_e32 v40, s33, v103
	v_add_u32_e32 v49, 0xffffff40, v48
	v_cndmask_b32_e32 v60, 0, v41, vcc
	v_add_u32_e32 v40, v40, v60
	v_lshl_add_u32 v66, v40, 10, v148
	v_add_u32_e32 v40, s8, v94
	v_add_u32_e32 v41, 0xffffff40, v40
	v_min_i32_e32 v41, s1, v41
	v_lshlrev_b32_e32 v41, 2, v41
	v_cmp_lt_i32_e32 vcc, s39, v40
	v_min_i32_e32 v49, s1, v49
	v_lshlrev_b32_e32 v49, 2, v49
	v_cndmask_b32_e32 v61, 0, v41, vcc
	v_cmp_lt_i32_e32 vcc, s39, v48
	s_or_b32 s9, s33, 1
	s_waitcnt lgkmcnt(0)
	s_barrier
	v_cndmask_b32_e32 v62, 0, v49, vcc
	v_add_u32_e32 v48, s9, v62
	v_lshl_add_u32 v68, v48, 10, v148
	v_add_u32_e32 v48, s8, v106
	v_min_i32_e32 v49, s1, v48
	v_lshlrev_b32_e32 v49, 2, v49
	v_cmp_lt_i32_e32 vcc, -1, v48
	v_or_b32_e32 v48, s33, v105
	v_add_u32_e32 v32, s33, v59
	v_cndmask_b32_e32 v63, 0, v49, vcc
	v_add_u32_e32 v40, s9, v61
	v_add_u32_e32 v48, v48, v63
	v_lshl_add_u32 v65, v32, 10, v148
	global_load_dwordx4 v[32:35], v64, s[92:93]
	global_load_dwordx4 v[36:39], v65, s[92:93]
	v_lshl_add_u32 v67, v40, 10, v148
	global_load_dwordx4 v[40:43], v66, s[92:93]
	global_load_dwordx4 v[44:47], v67, s[92:93]
	v_lshl_add_u32 v69, v48, 10, v148
	global_load_dwordx4 v[48:51], v68, s[92:93]
	global_load_dwordx4 v[52:55], v69, s[92:93]
	global_load_dwordx4 v[210:213], v64, s[94:95]
	global_load_dwordx4 v[214:217], v65, s[94:95]
	global_load_dwordx4 v[218:221], v66, s[94:95]
	global_load_dwordx4 v[222:225], v67, s[94:95]
	global_load_dwordx4 v[226:229], v68, s[94:95]
	global_load_dwordx4 v[230:233], v69, s[94:95]
	v_readlane_b32 s9, v243, 7
	s_or_b32 s9, s0, s9
	s_add_i32 s8, s33, s6
	s_lshl_b32 s8, s8, 10
	s_mov_b32 s12, 0
	s_waitcnt vmcnt(11)
	ds_write_b128 v138, v[32:35]
	s_waitcnt vmcnt(10)
	ds_write_b128 v139, v[36:39]
	s_waitcnt vmcnt(9)
	ds_write_b128 v142, v[40:43]
	s_waitcnt vmcnt(8)
	ds_write_b128 v140, v[44:47]
	s_waitcnt vmcnt(7)
	ds_write_b128 v138, v[48:51] offset:36864
	s_waitcnt vmcnt(6)
	ds_write_b128 v141, v[52:55]
	s_nop 0
	s_nop 0
	s_nop 0
	s_nop 0
	s_nop 0
	s_nop 0
	v_or_b32_e32 v65, s9, v73
	v_lshlrev_b32_e32 v64, 12, v65
	v_add3_u32 v64, v64, s8, v149
	v_or_b32_e32 v66, 64, v64
	s_waitcnt vmcnt(5)
	ds_write_b128 v138, v[210:213] offset:55296
	s_waitcnt vmcnt(4)
	ds_write_b128 v139, v[214:217] offset:55296
	s_waitcnt vmcnt(3)
	ds_write_b128 v142, v[218:221] offset:55296
	s_waitcnt vmcnt(2)
	ds_write_b128 v140, v[222:225] offset:55296
	s_waitcnt vmcnt(1)
	ds_write_b128 v99, v[226:229]
	s_waitcnt vmcnt(0)
	ds_write_b128 v141, v[230:233] offset:55296
	s_waitcnt lgkmcnt(0)
	s_barrier
	global_load_dwordx4 v[48:51], v64, s[90:91]
	global_load_dwordx4 v[52:55], v66, s[90:91]
	ds_bpermute_b32 v32, v88, v57
	ds_bpermute_b32 v33, v88, v56
	v_mov_b32_e32 v36, 0
	v_mov_b32_e32 v40, 0
	v_mov_b32_e32 v44, 0
	s_waitcnt lgkmcnt(1)
	v_add_f32_e32 v151, v57, v32
	s_waitcnt lgkmcnt(0)
	v_add_f32_e32 v153, v56, v33
	ds_bpermute_b32 v152, v89, v151
	ds_bpermute_b32 v154, v89, v153
	v_add_u32_e32 v33, 64, v65
	v_max_i32_e32 v32, 64, v65
	v_min_i32_e32 v33, s1, v33
	v_sub_u32_e32 v33, v33, v32
	v_add_u32_e32 v155, 64, v33
	v_add_u32_e32 v33, s0, v128
	v_mov_b32_e32 v56, 0
	v_sub_u32_e32 v156, v33, v32
	v_mov_b32_e32 v57, v133
	v_mov_b32_e32 v65, v129
	v_mov_b32_e32 v32, 0
	v_mov_b32_e32 v33, v56
	v_mov_b32_e32 v34, v56
	v_mov_b32_e32 v35, v56
	v_mov_b32_e32 v37, v56
	v_mov_b32_e32 v38, v56
	v_mov_b32_e32 v39, v56
	v_mov_b32_e32 v41, v56
	v_mov_b32_e32 v42, v56
	v_mov_b32_e32 v43, v56
	v_mov_b32_e32 v45, v56
	v_mov_b32_e32 v46, v56
	v_mov_b32_e32 v47, v56
.LBB0_1396:
	s_cmpk_eq_i32 s12, 0x80
	s_cselect_b32 s0, 0, 16
	v_add_u32_e32 v70, v132, v57
	s_add_i32 s0, s12, s0
	v_add_u32_e32 v71, s7, v65
	ds_read_b128 v[66:69], v70
	ds_read_b128 v[158:161], v70 offset:64
	v_add_u32_e32 v70, s0, v131
	ds_read_b64_tr_b16 v[162:163], v71 offset:55296
	ds_read_b64_tr_b16 v[166:167], v71 offset:55328
	ds_read_b64_tr_b16 v[170:171], v71 offset:55360
	ds_read_b64_tr_b16 v[174:175], v71 offset:55392
	v_add_u32_e32 v164, s0, v130
	v_mad_u64_u32 v[70:71], s[0:1], v70, s96, v[80:81]
	ds_read_b128 v[176:179], v70
	s_waitcnt vmcnt(1) lgkmcnt(6)
	v_mfma_f32_16x16x32_bf16 v[66:69], v[66:69], v[48:51], 0
	v_mad_u64_u32 v[184:185], s[0:1], v164, s96, v[84:85]
	v_add_u32_e32 v157, s12, v156
	s_waitcnt vmcnt(0) lgkmcnt(5)
	v_mfma_f32_16x16x32_bf16 v[66:69], v[158:161], v[52:55], v[66:69]
	ds_read_b128 v[158:161], v70 offset:64
	ds_read_b64_tr_b16 v[164:165], v184
	v_add_u32_e32 v186, 2, v157
	v_add_u32_e32 v187, 3, v157
	s_waitcnt lgkmcnt(2)
	v_mfma_f32_16x16x32_bf16 v[178:181], v[176:179], v[48:51], 0
	s_nop 1
	v_fma_f32 v68, v68, s4, -v150
	v_fma_f32 v69, v69, s4, -v150
	v_fma_f32 v66, v66, s4, -v150
	s_waitcnt lgkmcnt(1)
	v_mfma_f32_16x16x32_bf16 v[158:161], v[158:161], v[52:55], v[178:181]
	v_exp_f32_e32 v68, v68
	v_exp_f32_e32 v69, v69
	v_fma_f32 v67, v67, s4, -v150
	v_exp_f32_e32 v66, v66
	v_exp_f32_e32 v67, v67
	v_add_u32_e32 v183, 1, v157
	v_add_u32_e32 v188, 16, v157
	v_add_u32_e32 v189, 17, v157
	v_add_u32_e32 v190, 18, v157
	v_add_u32_e32 v191, 19, v157
	v_cmp_le_u32_e32 vcc, v157, v155
	v_cmp_le_u32_e64 s[8:9], v186, v155
	v_cmp_le_u32_e64 s[10:11], v187, v155
	v_fma_f32 v70, v158, s4, -v150
	v_fma_f32 v71, v159, s4, -v150
	v_fma_f32 v157, v160, s4, -v150
	v_fma_f32 v158, v161, s4, -v150
	v_cndmask_b32_e64 v161, 0, v68, s[8:9]
	v_cndmask_b32_e64 v178, 0, v69, s[10:11]
	v_exp_f32_e32 v68, v70
	v_exp_f32_e32 v69, v71
	v_exp_f32_e32 v70, v157
	v_exp_f32_e32 v71, v158
	ds_read_b64_tr_b16 v[168:169], v184 offset:32
	ds_read_b64_tr_b16 v[172:173], v184 offset:64
	ds_read_b64_tr_b16 v[176:177], v184 offset:96
	v_cmp_le_u32_e64 s[0:1], v183, v155
	v_cndmask_b32_e32 v159, 0, v66, vcc
	v_add_f32_e32 v56, v56, v159
	v_cndmask_b32_e64 v160, 0, v67, s[0:1]
	v_cmp_le_u32_e32 vcc, v188, v155
	v_cmp_le_u32_e64 s[0:1], v189, v155
	v_cmp_le_u32_e64 s[8:9], v190, v155
	v_cmp_le_u32_e64 s[10:11], v191, v155
	v_add_f32_e32 v56, v160, v56
	v_cndmask_b32_e32 v157, 0, v68, vcc
	v_cndmask_b32_e64 v158, 0, v69, s[0:1]
	v_cndmask_b32_e64 v70, 0, v70, s[8:9]
	v_cndmask_b32_e64 v71, 0, v71, s[10:11]
	v_add_f32_e32 v56, v161, v56
	v_cvt_pk_bf16_f32 v66, v159, v160
	v_cvt_pk_bf16_f32 v67, v161, v178
	v_cvt_pk_bf16_f32 v68, v157, v158
	v_cvt_pk_bf16_f32 v69, v70, v71
	v_add_f32_e32 v56, v178, v56
	v_add_f32_e32 v56, v157, v56
	s_waitcnt lgkmcnt(3)
	v_mfma_f32_16x16x32_bf16 v[44:47], v[162:165], v[66:69], v[44:47]
	v_add_f32_e32 v56, v158, v56
	s_add_i32 s12, s12, 32
	v_add_f32_e32 v56, v70, v56
	s_waitcnt lgkmcnt(2)
	v_mfma_f32_16x16x32_bf16 v[40:43], v[166:169], v[66:69], v[40:43]
	v_add_u32_e32 v65, 0x1200, v65
	v_add_u32_e32 v57, 0x1200, v57
	s_cmpk_lg_i32 s12, 0xa0
	s_waitcnt lgkmcnt(1)
	v_mfma_f32_16x16x32_bf16 v[36:39], v[170:173], v[66:69], v[36:39]
	v_add_f32_e32 v56, v71, v56
	s_waitcnt lgkmcnt(0)
	v_mfma_f32_16x16x32_bf16 v[32:35], v[174:177], v[66:69], v[32:35]
	s_cbranch_scc1 .LBB0_1396
	s_or_b32 s0, s33, 2
	v_add_u32_e32 v48, s0, v58
	v_or_b32_e32 v58, s0, v103
	s_or_b32 s1, s33, 3
	v_add_u32_e32 v58, v58, v60
	v_add_u32_e32 v62, s1, v62
	s_waitcnt lgkmcnt(0)
	s_barrier
	v_lshl_add_u32 v57, v48, 10, v148
	v_add_u32_e32 v48, s0, v59
	v_lshl_add_u32 v70, v58, 10, v148
	v_add_u32_e32 v58, s1, v61
	v_lshl_add_u32 v62, v62, 10, v148
	v_add3_u32 v63, s0, v105, v63
	v_lshl_add_u32 v65, v48, 10, v148
	global_load_dwordx4 v[48:51], v57, s[92:93]
	global_load_dwordx4 v[52:55], v65, s[92:93]
	v_lshl_add_u32 v71, v58, 10, v148
	global_load_dwordx4 v[58:61], v70, s[92:93]
	global_load_dwordx4 v[66:69], v71, s[92:93]
	v_lshl_add_u32 v63, v63, 10, v148
	global_load_dwordx4 v[158:161], v62, s[92:93]
	global_load_dwordx4 v[162:165], v63, s[92:93]
	global_load_dwordx4 v[210:213], v57, s[94:95]
	global_load_dwordx4 v[214:217], v65, s[94:95]
	global_load_dwordx4 v[218:221], v70, s[94:95]
	global_load_dwordx4 v[222:225], v71, s[94:95]
	global_load_dwordx4 v[226:229], v62, s[94:95]
	global_load_dwordx4 v[230:233], v63, s[94:95]
	s_mov_b32 s12, 0
	s_waitcnt vmcnt(11)
	ds_write_b128 v138, v[48:51]
	s_waitcnt vmcnt(10)
	ds_write_b128 v139, v[52:55]
	s_waitcnt vmcnt(9)
	ds_write_b128 v142, v[58:61]
	s_waitcnt vmcnt(8)
	ds_write_b128 v140, v[66:69]
	s_waitcnt vmcnt(7)
	ds_write_b128 v138, v[158:161] offset:36864
	s_waitcnt vmcnt(6)
	ds_write_b128 v141, v[162:165]
	s_nop 0
	s_nop 0
	s_nop 0
	s_nop 0
	s_nop 0
	s_nop 0
	v_add_u32_e32 v57, 0x800, v64
	v_add_u32_e32 v62, 0x840, v64
	s_waitcnt vmcnt(5)
	ds_write_b128 v138, v[210:213] offset:55296
	s_waitcnt vmcnt(4)
	ds_write_b128 v139, v[214:217] offset:55296
	s_waitcnt vmcnt(3)
	ds_write_b128 v142, v[218:221] offset:55296
	s_waitcnt vmcnt(2)
	ds_write_b128 v140, v[222:225] offset:55296
	s_waitcnt vmcnt(1)
	ds_write_b128 v99, v[226:229]
	s_waitcnt vmcnt(0)
	ds_write_b128 v141, v[230:233] offset:55296
	s_waitcnt lgkmcnt(0)
	s_barrier
	global_load_dwordx4 v[64:67], v57, s[90:91]
	global_load_dwordx4 v[68:71], v62, s[90:91]
	ds_bpermute_b32 v48, v88, v56
	v_mov_b32_e32 v160, 0
	v_mov_b32_e32 v159, v133
	v_mov_b32_e32 v161, v129
	v_mov_b32_e32 v49, v160
	s_waitcnt lgkmcnt(0)
	v_add_f32_e32 v157, v56, v48
	ds_bpermute_b32 v158, v89, v157
	v_mov_b32_e32 v48, 0
	v_mov_b32_e32 v50, v160
	v_mov_b32_e32 v51, v160
	v_mov_b32_e32 v52, 0
	v_mov_b32_e32 v53, v160
	v_mov_b32_e32 v54, v160
	v_mov_b32_e32 v55, v160
	v_mov_b32_e32 v56, 0
	v_mov_b32_e32 v57, v160
	v_mov_b32_e32 v58, v160
	v_mov_b32_e32 v59, v160
	v_mov_b32_e32 v60, 0
	v_mov_b32_e32 v61, v160
	v_mov_b32_e32 v62, v160
	v_mov_b32_e32 v63, v160
